# PRE adaLN modulation GEMV: next 8 weight rows requested into a second register set before the current 8 are consumed (loop unrolled by two, counted waits +8)
# speedup vs baseline: 1.0153x; 1.0023x over previous
.LBB0_827:
	v_and_b32_e32 v0, 0x3ff, v3
	v_lshlrev_b32_e32 v0, 2, v0
	v_cmp_gt_u32_e32 vcc, s75, v3
	v_lshl_add_u64 v[10:11], s[50:51], 0, v[0:1]
	s_movk_i32 s17, 0x12ff
	v_cndmask_b32_e32 v11, v11, v5, vcc
	v_cndmask_b32_e32 v10, v10, v4, vcc
	global_load_dword v0, v[10:11], off
	s_mov_b64 s[22:23], 0x400
	v_cmp_lt_u32_e32 vcc, s17, v3
	v_lshl_add_u64 v[4:5], v[4:5], 0, s[22:23]
	s_or_b64 s[20:21], vcc, s[20:21]
	s_waitcnt vmcnt(0)
	v_mul_f32_e32 v9, 0xbfb8aa3b, v0
	v_exp_f32_e32 v9, v9
	s_nop 0
	v_add_f32_e32 v9, 1.0, v9
	v_rcp_f32_e32 v9, v9
	s_nop 0
	v_mul_f32_e32 v0, v0, v9
	ds_write_b32 v8, v0
	v_add_u32_e32 v0, 0x100, v3
	v_add_u32_e32 v8, 0x400, v8
	v_mov_b32_e32 v3, v0
	s_andn2_b64 exec, exec, s[20:21]
	s_cbranch_execnz .LBB0_827
	s_or_b64 exec, exec, s[20:21]
	s_mov_b32 s17, 0x2aaaaaab
	v_mul_hi_i32 v0, v6, s17
	v_lshrrev_b32_e32 v3, 31, v0
	v_ashrrev_i32_e32 v0, 3, v0
	v_add_u32_e32 v0, v0, v3
	v_mul_lo_u32 v3, v0, 48
	v_sub_u32_e32 v3, v6, v3
	v_lshlrev_b32_e32 v34, 7, v3
	v_and_b32_e32 v3, 0x380, v2
	v_or_b32_e32 v2, 0x7f, v2
	v_sub_u32_e32 v2, v2, v3
	v_add_u32_e32 v31, 1, v2
	v_lshrrev_b32_e32 v2, 5, v32
	v_mul_hi_u32_u24_e32 v3, 0x300000, v2
	v_mul_u32_u24_e32 v2, 0x300000, v2
	v_mad_i64_i32 v[2:3], s[20:21], v0, s35, v[2:3]
	v_and_b32_e32 v4, 31, v7
	v_ashrrev_i32_e32 v35, 31, v34
	v_lshl_or_b32 v2, v4, 4, v2
	v_readlane_b32 s20, v255, 26
	v_lshl_add_u64 v[2:3], v[34:35], 2, v[2:3]
	v_readlane_b32 s21, v255, 27
	s_waitcnt lgkmcnt(0)
	s_barrier
	v_lshl_add_u64 v[36:37], s[20:21], 0, v[2:3]
	v_lshlrev_b32_e32 v2, 4, v32
	v_and_b32_e32 v2, 0xe00, v2
	v_add_u32_e32 v35, v38, v2
	v_mov_b32_e32 v2, 0
	s_mov_b64 s[20:21], 0
	v_mov_b32_e32 v3, v2
	v_mov_b32_e32 v4, v2
	v_mov_b32_e32 v5, v2
	v_mov_b32_e32 v18, v2
	v_mov_b32_e32 v19, v2
	v_mov_b32_e32 v20, v2
	v_mov_b32_e32 v21, v2
	v_mov_b32_e32 v14, v2
	v_mov_b32_e32 v15, v2
	v_mov_b32_e32 v16, v2
	v_mov_b32_e32 v17, v2
	v_mov_b32_e32 v10, v2
	v_mov_b32_e32 v11, v2
	v_mov_b32_e32 v12, v2
	v_mov_b32_e32 v13, v2
	v_mov_b32_e32 v6, v2
	v_mov_b32_e32 v7, v2
	v_mov_b32_e32 v8, v2
	v_mov_b32_e32 v9, v2
	s_movk_i32 s39, 16
	s_mov_b32 s17, 0xfffd6000
	v_add_co_u32_e32 v22, vcc, s17, v36
	s_mov_b32 s17, 0xfffdc000
	s_nop 0
	v_addc_co_u32_e32 v23, vcc, -1, v37, vcc
	v_add_co_u32_e32 v68, vcc, s17, v36
	s_mov_b32 s17, 0xfffe2000
	s_nop 0
	v_addc_co_u32_e32 v69, vcc, -1, v37, vcc
	v_add_co_u32_e32 v72, vcc, s17, v36
	s_mov_b32 s17, 0xfffe8000
	s_nop 0
	v_addc_co_u32_e32 v73, vcc, -1, v37, vcc
	v_add_co_u32_e32 v76, vcc, s17, v36
	global_load_dwordx4 v[22:25], v[22:23], off nt
	s_nop 0
	v_addc_co_u32_e32 v77, vcc, -1, v37, vcc
	s_mov_b32 s17, 0xfffee000
	global_load_dwordx4 v[68:71], v[68:69], off nt
	v_add_co_u32_e32 v80, vcc, s17, v36
	global_load_dwordx4 v[72:75], v[72:73], off nt
	s_nop 0
	v_addc_co_u32_e32 v81, vcc, -1, v37, vcc
	s_mov_b32 s17, 0xffff4000
	global_load_dwordx4 v[76:79], v[76:77], off nt
	v_add_co_u32_e32 v100, vcc, s17, v36
	global_load_dwordx4 v[80:83], v[80:81], off nt
	s_nop 0
	v_addc_co_u32_e32 v101, vcc, -1, v37, vcc
	s_movk_i32 s17, 0xa000
	global_load_dwordx4 v[100:103], v[100:101], off nt
	v_add_co_u32_e32 v104, vcc, s17, v36
	s_nop 1
	v_addc_co_u32_e32 v105, vcc, -1, v37, vcc
	global_load_dwordx4 v[104:107], v[104:105], off nt
	s_nop 0
	global_load_dwordx4 v[108:111], v[36:37], off nt
	s_mov_b64 s[22:23], 0x30000
	v_lshl_add_u64 v[36:37], v[36:37], 0, s[22:23]
.LBB0_829:
	s_mov_b32 s17, 0xfffd6000
	v_add_co_u32_e32 v116, vcc, s17, v36
	s_mov_b32 s17, 0xfffdc000
	s_nop 0
	v_addc_co_u32_e32 v117, vcc, -1, v37, vcc
	v_add_co_u32_e32 v120, vcc, s17, v36
	s_mov_b32 s17, 0xfffe2000
	s_nop 0
	v_addc_co_u32_e32 v121, vcc, -1, v37, vcc
	v_add_co_u32_e32 v124, vcc, s17, v36
	s_mov_b32 s17, 0xfffe8000
	s_nop 0
	v_addc_co_u32_e32 v125, vcc, -1, v37, vcc
	v_add_co_u32_e32 v128, vcc, s17, v36
	global_load_dwordx4 v[116:119], v[116:117], off nt
	s_nop 0
	v_addc_co_u32_e32 v129, vcc, -1, v37, vcc
	s_mov_b32 s17, 0xfffee000
	global_load_dwordx4 v[120:123], v[120:121], off nt
	v_add_co_u32_e32 v132, vcc, s17, v36
	global_load_dwordx4 v[124:127], v[124:125], off nt
	s_nop 0
	v_addc_co_u32_e32 v133, vcc, -1, v37, vcc
	s_mov_b32 s17, 0xffff4000
	global_load_dwordx4 v[128:131], v[128:129], off nt
	v_add_co_u32_e32 v136, vcc, s17, v36
	global_load_dwordx4 v[132:135], v[132:133], off nt
	s_nop 0
	v_addc_co_u32_e32 v137, vcc, -1, v37, vcc
	s_movk_i32 s17, 0xa000
	global_load_dwordx4 v[136:139], v[136:137], off nt
	v_add_co_u32_e32 v140, vcc, s17, v36
	s_nop 1
	v_addc_co_u32_e32 v141, vcc, -1, v37, vcc
	global_load_dwordx4 v[140:143], v[140:141], off nt
	s_nop 0
	global_load_dwordx4 v[144:147], v[36:37], off nt
	s_cmp_gt_u32 s39, 2
	s_cselect_b32 s22, 0x30000, 0
	s_mov_b32 s23, 0
	s_add_i32 s39, s39, -1
	v_lshl_add_u64 v[36:37], v[36:37], 0, s[22:23]
	ds_read_b128 v[44:47], v35
	ds_read_b128 v[48:51], v35 offset:16
	ds_read_b128 v[52:55], v35 offset:4096
	ds_read_b128 v[56:59], v35 offset:8192
	ds_read_b128 v[60:63], v35 offset:12288
	ds_read_b128 v[64:67], v35 offset:16384
	ds_read_b128 v[84:87], v35 offset:4112
	ds_read_b128 v[88:91], v35 offset:8208
	ds_read_b128 v[92:95], v35 offset:12304
	ds_read_b128 v[96:99], v35 offset:16400
	s_waitcnt lgkmcnt(9)
	v_mov_b32_e32 v112, v47
	v_add_u32_e32 v31, -8, v31
	s_waitcnt lgkmcnt(8)
	v_mov_b32_e32 v114, v51
	v_cmp_eq_u32_e32 vcc, 0, v31
	v_add_u32_e32 v35, 32, v35
	s_or_b64 s[20:21], vcc, s[20:21]
	s_waitcnt vmcnt(15) lgkmcnt(7)
	v_pk_fma_f32 v[18:19], v[22:23], v[52:53], v[18:19] op_sel_hi:[1,0,1]
	v_pk_fma_f32 v[20:21], v[24:25], v[52:53], v[20:21] op_sel_hi:[1,0,1]
	v_pk_fma_f32 v[2:3], v[22:23], v[44:45], v[2:3] op_sel_hi:[1,0,1]
	v_pk_fma_f32 v[4:5], v[24:25], v[44:45], v[4:5] op_sel_hi:[1,0,1]
	s_waitcnt lgkmcnt(6)
	v_pk_fma_f32 v[14:15], v[22:23], v[56:57], v[14:15] op_sel_hi:[1,0,1]
	s_waitcnt vmcnt(14)
	v_pk_fma_f32 v[18:19], v[68:69], v[52:53], v[18:19] op_sel:[0,1,0]
	v_pk_fma_f32 v[20:21], v[70:71], v[52:53], v[20:21] op_sel:[0,1,0]
	v_pk_fma_f32 v[16:17], v[24:25], v[56:57], v[16:17] op_sel_hi:[1,0,1]
	v_pk_fma_f32 v[2:3], v[68:69], v[44:45], v[2:3] op_sel:[0,1,0]
	v_pk_fma_f32 v[4:5], v[70:71], v[44:45], v[4:5] op_sel:[0,1,0]
	s_waitcnt vmcnt(13)
	v_pk_fma_f32 v[18:19], v[72:73], v[54:55], v[18:19] op_sel_hi:[1,0,1]
	v_mov_b32_e32 v44, v55
	v_pk_fma_f32 v[20:21], v[74:75], v[54:55], v[20:21] op_sel_hi:[1,0,1]
	v_pk_fma_f32 v[14:15], v[68:69], v[56:57], v[14:15] op_sel:[0,1,0]
	v_pk_fma_f32 v[16:17], v[70:71], v[56:57], v[16:17] op_sel:[0,1,0]
	s_waitcnt lgkmcnt(5)
	v_pk_fma_f32 v[10:11], v[22:23], v[60:61], v[10:11] op_sel_hi:[1,0,1]
	v_pk_fma_f32 v[12:13], v[24:25], v[60:61], v[12:13] op_sel_hi:[1,0,1]
	s_waitcnt lgkmcnt(4)
	v_pk_fma_f32 v[6:7], v[22:23], v[64:65], v[6:7] op_sel_hi:[1,0,1]
	v_pk_fma_f32 v[8:9], v[24:25], v[64:65], v[8:9] op_sel_hi:[1,0,1]
	s_waitcnt vmcnt(12)
	v_pk_fma_f32 v[18:19], v[76:77], v[44:45], v[18:19] op_sel_hi:[1,0,1]
	v_pk_fma_f32 v[20:21], v[78:79], v[44:45], v[20:21] op_sel_hi:[1,0,1]
	v_pk_fma_f32 v[14:15], v[72:73], v[58:59], v[14:15] op_sel_hi:[1,0,1]
	v_mov_b32_e32 v44, v59
	v_pk_fma_f32 v[16:17], v[74:75], v[58:59], v[16:17] op_sel_hi:[1,0,1]
	v_pk_fma_f32 v[10:11], v[68:69], v[60:61], v[10:11] op_sel:[0,1,0]
	v_pk_fma_f32 v[12:13], v[70:71], v[60:61], v[12:13] op_sel:[0,1,0]
	v_pk_fma_f32 v[6:7], v[68:69], v[64:65], v[6:7] op_sel:[0,1,0]
	v_pk_fma_f32 v[8:9], v[70:71], v[64:65], v[8:9] op_sel:[0,1,0]
	v_pk_fma_f32 v[2:3], v[72:73], v[46:47], v[2:3] op_sel_hi:[1,0,1]
	v_pk_fma_f32 v[4:5], v[74:75], v[46:47], v[4:5] op_sel_hi:[1,0,1]
	s_waitcnt vmcnt(11) lgkmcnt(3)
	v_pk_fma_f32 v[18:19], v[80:81], v[84:85], v[18:19] op_sel_hi:[1,0,1]
	v_pk_fma_f32 v[20:21], v[82:83], v[84:85], v[20:21] op_sel_hi:[1,0,1]
	v_pk_fma_f32 v[14:15], v[76:77], v[44:45], v[14:15] op_sel_hi:[1,0,1]
	v_pk_fma_f32 v[16:17], v[78:79], v[44:45], v[16:17] op_sel_hi:[1,0,1]
	v_pk_fma_f32 v[10:11], v[72:73], v[62:63], v[10:11] op_sel_hi:[1,0,1]
	v_mov_b32_e32 v44, v63
	v_pk_fma_f32 v[12:13], v[74:75], v[62:63], v[12:13] op_sel_hi:[1,0,1]
	v_pk_fma_f32 v[6:7], v[72:73], v[66:67], v[6:7] op_sel_hi:[1,0,1]
	v_mov_b32_e32 v22, v67
	v_pk_fma_f32 v[8:9], v[74:75], v[66:67], v[8:9] op_sel_hi:[1,0,1]
	v_pk_fma_f32 v[2:3], v[76:77], v[112:113], v[2:3] op_sel_hi:[1,0,1]
	v_pk_fma_f32 v[4:5], v[78:79], v[112:113], v[4:5] op_sel_hi:[1,0,1]
	s_waitcnt vmcnt(10)
	v_pk_fma_f32 v[18:19], v[100:101], v[84:85], v[18:19] op_sel:[0,1,0]
	v_pk_fma_f32 v[20:21], v[102:103], v[84:85], v[20:21] op_sel:[0,1,0]
	s_waitcnt lgkmcnt(2)
	v_pk_fma_f32 v[14:15], v[80:81], v[88:89], v[14:15] op_sel_hi:[1,0,1]
	v_pk_fma_f32 v[16:17], v[82:83], v[88:89], v[16:17] op_sel_hi:[1,0,1]
	v_pk_fma_f32 v[10:11], v[76:77], v[44:45], v[10:11] op_sel_hi:[1,0,1]
	v_pk_fma_f32 v[12:13], v[78:79], v[44:45], v[12:13] op_sel_hi:[1,0,1]
	v_pk_fma_f32 v[6:7], v[76:77], v[22:23], v[6:7] op_sel_hi:[1,0,1]
	v_pk_fma_f32 v[8:9], v[78:79], v[22:23], v[8:9] op_sel_hi:[1,0,1]
	v_pk_fma_f32 v[2:3], v[80:81], v[48:49], v[2:3] op_sel_hi:[1,0,1]
	v_pk_fma_f32 v[4:5], v[82:83], v[48:49], v[4:5] op_sel_hi:[1,0,1]
	s_waitcnt vmcnt(9)
	v_pk_fma_f32 v[18:19], v[104:105], v[86:87], v[18:19] op_sel_hi:[1,0,1]
	v_mov_b32_e32 v46, v87
	v_pk_fma_f32 v[20:21], v[106:107], v[86:87], v[20:21] op_sel_hi:[1,0,1]
	v_pk_fma_f32 v[14:15], v[100:101], v[88:89], v[14:15] op_sel:[0,1,0]
	v_pk_fma_f32 v[16:17], v[102:103], v[88:89], v[16:17] op_sel:[0,1,0]
	s_waitcnt lgkmcnt(1)
	v_pk_fma_f32 v[10:11], v[80:81], v[92:93], v[10:11] op_sel_hi:[1,0,1]
	v_pk_fma_f32 v[12:13], v[82:83], v[92:93], v[12:13] op_sel_hi:[1,0,1]
	s_waitcnt lgkmcnt(0)
	v_pk_fma_f32 v[6:7], v[80:81], v[96:97], v[6:7] op_sel_hi:[1,0,1]
	v_pk_fma_f32 v[8:9], v[82:83], v[96:97], v[8:9] op_sel_hi:[1,0,1]
	v_pk_fma_f32 v[2:3], v[100:101], v[48:49], v[2:3] op_sel:[0,1,0]
	v_pk_fma_f32 v[4:5], v[102:103], v[48:49], v[4:5] op_sel:[0,1,0]
	s_waitcnt vmcnt(8)
	v_pk_fma_f32 v[18:19], v[108:109], v[46:47], v[18:19] op_sel_hi:[1,0,1]
	v_pk_fma_f32 v[20:21], v[110:111], v[46:47], v[20:21] op_sel_hi:[1,0,1]
	v_pk_fma_f32 v[14:15], v[104:105], v[90:91], v[14:15] op_sel_hi:[1,0,1]
	v_mov_b32_e32 v46, v91
	v_pk_fma_f32 v[16:17], v[106:107], v[90:91], v[16:17] op_sel_hi:[1,0,1]
	v_pk_fma_f32 v[10:11], v[100:101], v[92:93], v[10:11] op_sel:[0,1,0]
	v_pk_fma_f32 v[12:13], v[102:103], v[92:93], v[12:13] op_sel:[0,1,0]
	v_pk_fma_f32 v[6:7], v[100:101], v[96:97], v[6:7] op_sel:[0,1,0]
	v_pk_fma_f32 v[8:9], v[102:103], v[96:97], v[8:9] op_sel:[0,1,0]
	v_pk_fma_f32 v[2:3], v[104:105], v[50:51], v[2:3] op_sel_hi:[1,0,1]
	v_pk_fma_f32 v[4:5], v[106:107], v[50:51], v[4:5] op_sel_hi:[1,0,1]
	v_pk_fma_f32 v[14:15], v[108:109], v[46:47], v[14:15] op_sel_hi:[1,0,1]
	v_pk_fma_f32 v[16:17], v[110:111], v[46:47], v[16:17] op_sel_hi:[1,0,1]
	v_pk_fma_f32 v[10:11], v[104:105], v[94:95], v[10:11] op_sel_hi:[1,0,1]
	v_mov_b32_e32 v46, v95
	v_pk_fma_f32 v[12:13], v[106:107], v[94:95], v[12:13] op_sel_hi:[1,0,1]
	v_pk_fma_f32 v[6:7], v[104:105], v[98:99], v[6:7] op_sel_hi:[1,0,1]
	v_mov_b32_e32 v44, v99
	v_pk_fma_f32 v[8:9], v[106:107], v[98:99], v[8:9] op_sel_hi:[1,0,1]
	v_pk_fma_f32 v[2:3], v[108:109], v[114:115], v[2:3] op_sel_hi:[1,0,1]
	v_pk_fma_f32 v[4:5], v[110:111], v[114:115], v[4:5] op_sel_hi:[1,0,1]
	v_pk_fma_f32 v[10:11], v[108:109], v[46:47], v[10:11] op_sel_hi:[1,0,1]
	v_pk_fma_f32 v[12:13], v[110:111], v[46:47], v[12:13] op_sel_hi:[1,0,1]
	v_pk_fma_f32 v[6:7], v[108:109], v[44:45], v[6:7] op_sel_hi:[1,0,1]
	v_pk_fma_f32 v[8:9], v[110:111], v[44:45], v[8:9] op_sel_hi:[1,0,1]
	s_mov_b32 s17, 0xfffd6000
	v_add_co_u32_e32 v22, vcc, s17, v36
	s_mov_b32 s17, 0xfffdc000
	s_nop 0
	v_addc_co_u32_e32 v23, vcc, -1, v37, vcc
	v_add_co_u32_e32 v68, vcc, s17, v36
	s_mov_b32 s17, 0xfffe2000
	s_nop 0
	v_addc_co_u32_e32 v69, vcc, -1, v37, vcc
	v_add_co_u32_e32 v72, vcc, s17, v36
	s_mov_b32 s17, 0xfffe8000
	s_nop 0
	v_addc_co_u32_e32 v73, vcc, -1, v37, vcc
	v_add_co_u32_e32 v76, vcc, s17, v36
	global_load_dwordx4 v[22:25], v[22:23], off nt
	s_nop 0
	v_addc_co_u32_e32 v77, vcc, -1, v37, vcc
	s_mov_b32 s17, 0xfffee000
	global_load_dwordx4 v[68:71], v[68:69], off nt
	v_add_co_u32_e32 v80, vcc, s17, v36
	global_load_dwordx4 v[72:75], v[72:73], off nt
	s_nop 0
	v_addc_co_u32_e32 v81, vcc, -1, v37, vcc
	s_mov_b32 s17, 0xffff4000
	global_load_dwordx4 v[76:79], v[76:77], off nt
	v_add_co_u32_e32 v100, vcc, s17, v36
	global_load_dwordx4 v[80:83], v[80:81], off nt
	s_nop 0
	v_addc_co_u32_e32 v101, vcc, -1, v37, vcc
	s_movk_i32 s17, 0xa000
	global_load_dwordx4 v[100:103], v[100:101], off nt
	v_add_co_u32_e32 v104, vcc, s17, v36
	s_nop 1
	v_addc_co_u32_e32 v105, vcc, -1, v37, vcc
	global_load_dwordx4 v[104:107], v[104:105], off nt
	s_nop 0
	global_load_dwordx4 v[108:111], v[36:37], off nt
	s_cmp_gt_u32 s39, 2
	s_cselect_b32 s22, 0x30000, 0
	s_mov_b32 s23, 0
	s_add_i32 s39, s39, -1
	v_lshl_add_u64 v[36:37], v[36:37], 0, s[22:23]
	ds_read_b128 v[44:47], v35
	ds_read_b128 v[48:51], v35 offset:16
	ds_read_b128 v[52:55], v35 offset:4096
	ds_read_b128 v[56:59], v35 offset:8192
	ds_read_b128 v[60:63], v35 offset:12288
	ds_read_b128 v[64:67], v35 offset:16384
	ds_read_b128 v[84:87], v35 offset:4112
	ds_read_b128 v[88:91], v35 offset:8208
	ds_read_b128 v[92:95], v35 offset:12304
	ds_read_b128 v[96:99], v35 offset:16400
	s_waitcnt lgkmcnt(9)
	v_mov_b32_e32 v112, v47
	v_add_u32_e32 v31, -8, v31
	s_waitcnt lgkmcnt(8)
	v_mov_b32_e32 v114, v51
	v_cmp_eq_u32_e32 vcc, 0, v31
	v_add_u32_e32 v35, 32, v35
	s_or_b64 s[20:21], vcc, s[20:21]
	s_waitcnt vmcnt(15) lgkmcnt(7)
	v_pk_fma_f32 v[18:19], v[116:117], v[52:53], v[18:19] op_sel_hi:[1,0,1]
	v_pk_fma_f32 v[20:21], v[118:119], v[52:53], v[20:21] op_sel_hi:[1,0,1]
	v_pk_fma_f32 v[2:3], v[116:117], v[44:45], v[2:3] op_sel_hi:[1,0,1]
	v_pk_fma_f32 v[4:5], v[118:119], v[44:45], v[4:5] op_sel_hi:[1,0,1]
	s_waitcnt lgkmcnt(6)
	v_pk_fma_f32 v[14:15], v[116:117], v[56:57], v[14:15] op_sel_hi:[1,0,1]
	s_waitcnt vmcnt(14)
	v_pk_fma_f32 v[18:19], v[120:121], v[52:53], v[18:19] op_sel:[0,1,0]
	v_pk_fma_f32 v[20:21], v[122:123], v[52:53], v[20:21] op_sel:[0,1,0]
	v_pk_fma_f32 v[16:17], v[118:119], v[56:57], v[16:17] op_sel_hi:[1,0,1]
	v_pk_fma_f32 v[2:3], v[120:121], v[44:45], v[2:3] op_sel:[0,1,0]
	v_pk_fma_f32 v[4:5], v[122:123], v[44:45], v[4:5] op_sel:[0,1,0]
	s_waitcnt vmcnt(13)
	v_pk_fma_f32 v[18:19], v[124:125], v[54:55], v[18:19] op_sel_hi:[1,0,1]
	v_mov_b32_e32 v44, v55
	v_pk_fma_f32 v[20:21], v[126:127], v[54:55], v[20:21] op_sel_hi:[1,0,1]
	v_pk_fma_f32 v[14:15], v[120:121], v[56:57], v[14:15] op_sel:[0,1,0]
	v_pk_fma_f32 v[16:17], v[122:123], v[56:57], v[16:17] op_sel:[0,1,0]
	s_waitcnt lgkmcnt(5)
	v_pk_fma_f32 v[10:11], v[116:117], v[60:61], v[10:11] op_sel_hi:[1,0,1]
	v_pk_fma_f32 v[12:13], v[118:119], v[60:61], v[12:13] op_sel_hi:[1,0,1]
	s_waitcnt lgkmcnt(4)
	v_pk_fma_f32 v[6:7], v[116:117], v[64:65], v[6:7] op_sel_hi:[1,0,1]
	v_pk_fma_f32 v[8:9], v[118:119], v[64:65], v[8:9] op_sel_hi:[1,0,1]
	s_waitcnt vmcnt(12)
	v_pk_fma_f32 v[18:19], v[128:129], v[44:45], v[18:19] op_sel_hi:[1,0,1]
	v_pk_fma_f32 v[20:21], v[130:131], v[44:45], v[20:21] op_sel_hi:[1,0,1]
	v_pk_fma_f32 v[14:15], v[124:125], v[58:59], v[14:15] op_sel_hi:[1,0,1]
	v_mov_b32_e32 v44, v59
	v_pk_fma_f32 v[16:17], v[126:127], v[58:59], v[16:17] op_sel_hi:[1,0,1]
	v_pk_fma_f32 v[10:11], v[120:121], v[60:61], v[10:11] op_sel:[0,1,0]
	v_pk_fma_f32 v[12:13], v[122:123], v[60:61], v[12:13] op_sel:[0,1,0]
	v_pk_fma_f32 v[6:7], v[120:121], v[64:65], v[6:7] op_sel:[0,1,0]
	v_pk_fma_f32 v[8:9], v[122:123], v[64:65], v[8:9] op_sel:[0,1,0]
	v_pk_fma_f32 v[2:3], v[124:125], v[46:47], v[2:3] op_sel_hi:[1,0,1]
	v_pk_fma_f32 v[4:5], v[126:127], v[46:47], v[4:5] op_sel_hi:[1,0,1]
	s_waitcnt vmcnt(11) lgkmcnt(3)
	v_pk_fma_f32 v[18:19], v[132:133], v[84:85], v[18:19] op_sel_hi:[1,0,1]
	v_pk_fma_f32 v[20:21], v[134:135], v[84:85], v[20:21] op_sel_hi:[1,0,1]
	v_pk_fma_f32 v[14:15], v[128:129], v[44:45], v[14:15] op_sel_hi:[1,0,1]
	v_pk_fma_f32 v[16:17], v[130:131], v[44:45], v[16:17] op_sel_hi:[1,0,1]
	v_pk_fma_f32 v[10:11], v[124:125], v[62:63], v[10:11] op_sel_hi:[1,0,1]
	v_mov_b32_e32 v44, v63
	v_pk_fma_f32 v[12:13], v[126:127], v[62:63], v[12:13] op_sel_hi:[1,0,1]
	v_pk_fma_f32 v[6:7], v[124:125], v[66:67], v[6:7] op_sel_hi:[1,0,1]
	v_mov_b32_e32 v116, v67
	v_pk_fma_f32 v[8:9], v[126:127], v[66:67], v[8:9] op_sel_hi:[1,0,1]
	v_pk_fma_f32 v[2:3], v[128:129], v[112:113], v[2:3] op_sel_hi:[1,0,1]
	v_pk_fma_f32 v[4:5], v[130:131], v[112:113], v[4:5] op_sel_hi:[1,0,1]
	s_waitcnt vmcnt(10)
	v_pk_fma_f32 v[18:19], v[136:137], v[84:85], v[18:19] op_sel:[0,1,0]
	v_pk_fma_f32 v[20:21], v[138:139], v[84:85], v[20:21] op_sel:[0,1,0]
	s_waitcnt lgkmcnt(2)
	v_pk_fma_f32 v[14:15], v[132:133], v[88:89], v[14:15] op_sel_hi:[1,0,1]
	v_pk_fma_f32 v[16:17], v[134:135], v[88:89], v[16:17] op_sel_hi:[1,0,1]
	v_pk_fma_f32 v[10:11], v[128:129], v[44:45], v[10:11] op_sel_hi:[1,0,1]
	v_pk_fma_f32 v[12:13], v[130:131], v[44:45], v[12:13] op_sel_hi:[1,0,1]
	v_pk_fma_f32 v[6:7], v[128:129], v[116:117], v[6:7] op_sel_hi:[1,0,1]
	v_pk_fma_f32 v[8:9], v[130:131], v[116:117], v[8:9] op_sel_hi:[1,0,1]
	v_pk_fma_f32 v[2:3], v[132:133], v[48:49], v[2:3] op_sel_hi:[1,0,1]
	v_pk_fma_f32 v[4:5], v[134:135], v[48:49], v[4:5] op_sel_hi:[1,0,1]
	s_waitcnt vmcnt(9)
	v_pk_fma_f32 v[18:19], v[140:141], v[86:87], v[18:19] op_sel_hi:[1,0,1]
	v_mov_b32_e32 v46, v87
	v_pk_fma_f32 v[20:21], v[142:143], v[86:87], v[20:21] op_sel_hi:[1,0,1]
	v_pk_fma_f32 v[14:15], v[136:137], v[88:89], v[14:15] op_sel:[0,1,0]
	v_pk_fma_f32 v[16:17], v[138:139], v[88:89], v[16:17] op_sel:[0,1,0]
	s_waitcnt lgkmcnt(1)
	v_pk_fma_f32 v[10:11], v[132:133], v[92:93], v[10:11] op_sel_hi:[1,0,1]
	v_pk_fma_f32 v[12:13], v[134:135], v[92:93], v[12:13] op_sel_hi:[1,0,1]
	s_waitcnt lgkmcnt(0)
	v_pk_fma_f32 v[6:7], v[132:133], v[96:97], v[6:7] op_sel_hi:[1,0,1]
	v_pk_fma_f32 v[8:9], v[134:135], v[96:97], v[8:9] op_sel_hi:[1,0,1]
	v_pk_fma_f32 v[2:3], v[136:137], v[48:49], v[2:3] op_sel:[0,1,0]
	v_pk_fma_f32 v[4:5], v[138:139], v[48:49], v[4:5] op_sel:[0,1,0]
	s_waitcnt vmcnt(8)
	v_pk_fma_f32 v[18:19], v[144:145], v[46:47], v[18:19] op_sel_hi:[1,0,1]
	v_pk_fma_f32 v[20:21], v[146:147], v[46:47], v[20:21] op_sel_hi:[1,0,1]
	v_pk_fma_f32 v[14:15], v[140:141], v[90:91], v[14:15] op_sel_hi:[1,0,1]
	v_mov_b32_e32 v46, v91
	v_pk_fma_f32 v[16:17], v[142:143], v[90:91], v[16:17] op_sel_hi:[1,0,1]
	v_pk_fma_f32 v[10:11], v[136:137], v[92:93], v[10:11] op_sel:[0,1,0]
	v_pk_fma_f32 v[12:13], v[138:139], v[92:93], v[12:13] op_sel:[0,1,0]
	v_pk_fma_f32 v[6:7], v[136:137], v[96:97], v[6:7] op_sel:[0,1,0]
	v_pk_fma_f32 v[8:9], v[138:139], v[96:97], v[8:9] op_sel:[0,1,0]
	v_pk_fma_f32 v[2:3], v[140:141], v[50:51], v[2:3] op_sel_hi:[1,0,1]
	v_pk_fma_f32 v[4:5], v[142:143], v[50:51], v[4:5] op_sel_hi:[1,0,1]
	v_pk_fma_f32 v[14:15], v[144:145], v[46:47], v[14:15] op_sel_hi:[1,0,1]
	v_pk_fma_f32 v[16:17], v[146:147], v[46:47], v[16:17] op_sel_hi:[1,0,1]
	v_pk_fma_f32 v[10:11], v[140:141], v[94:95], v[10:11] op_sel_hi:[1,0,1]
	v_mov_b32_e32 v46, v95
	v_pk_fma_f32 v[12:13], v[142:143], v[94:95], v[12:13] op_sel_hi:[1,0,1]
	v_pk_fma_f32 v[6:7], v[140:141], v[98:99], v[6:7] op_sel_hi:[1,0,1]
	v_mov_b32_e32 v44, v99
	v_pk_fma_f32 v[8:9], v[142:143], v[98:99], v[8:9] op_sel_hi:[1,0,1]
	v_pk_fma_f32 v[2:3], v[144:145], v[114:115], v[2:3] op_sel_hi:[1,0,1]
	v_pk_fma_f32 v[4:5], v[146:147], v[114:115], v[4:5] op_sel_hi:[1,0,1]
	v_pk_fma_f32 v[10:11], v[144:145], v[46:47], v[10:11] op_sel_hi:[1,0,1]
	v_pk_fma_f32 v[12:13], v[146:147], v[46:47], v[12:13] op_sel_hi:[1,0,1]
	v_pk_fma_f32 v[6:7], v[144:145], v[44:45], v[6:7] op_sel_hi:[1,0,1]
	v_pk_fma_f32 v[8:9], v[146:147], v[44:45], v[8:9] op_sel_hi:[1,0,1]
	s_andn2_b64 exec, exec, s[20:21]
	s_cbranch_execnz .LBB0_829
	s_or_b64 exec, exec, s[20:21]
	s_waitcnt vmcnt(0)
	s_movk_i32 s17, 0x50
	v_mad_u32_u24 v22, v32, s17, v38
	s_movk_i32 s17, 0x1800
	ds_write_b128 v22, v[2:5] offset:20480
	ds_write_b128 v22, v[18:21] offset:20496
	ds_write_b128 v22, v[14:17] offset:20512
	ds_write_b128 v22, v[10:13] offset:20528
	ds_write_b128 v22, v[6:9] offset:20544
	v_mul_lo_u32 v2, v0, s17
	v_lshl_add_u32 v0, v0, 2, v0
	s_mov_b64 s[20:21], 0
	s_waitcnt lgkmcnt(0)
	s_barrier
